# dft row-1024 job: next row loads prefetched one iteration ahead (counted vmcnt) instead of load-wait per row
# speedup vs baseline: 1.0274x; 1.0031x over previous
; __device__ __forceinline__ bf16_t f2bf(float f) { unsigned u = __float_as_uint(f); u += 0x7FFFu + ((u >> 16) & 1u); return (bf16_t)(u >> 16); }
; __device__ __forceinline__ float bflo(unsigned w) { return __uint_as_float(w << 16); }
; __device__ __forceinline__ float bfhi(unsigned w) { return __uint_as_float(w & 0xffff0000u); }
; __device__ __forceinline__ int tid_() { int t = threadIdx.x; asm volatile("" : "+v"(t)); return t; }
; __device__ void dft_row1024_job(const int bid, const int nblk, const bf16_t* __restrict__ YT, bf16_t* __restrict__ F, int CB) {
;     const int wid = tid_() >> 6, lane = tid_() & 63;
;     const int nrow = CB * DM;
;     for (int r = bid * 8 + wid; r < nrow; r += nblk * 8) {
;         const bf16_t* y = YT + (long)r * (2 * SEQ) + lane * 8;
;         float s = 0.f;
; #pragma unroll
;         for (int i = 0; i < 4; ++i) { const u32x4 w = *(const u32x4*)(y + i * 512);
; #pragma unroll
;             for (int k = 0; k < 4; ++k) s += bflo(w[k]) - bfhi(w[k]); }
;         s = wave_sum(s);
;         if (lane == 0) { const int bi = r >> 10, gc = r & 1023; F[((long)bi * SEQ + 1024) * DM + gc] = f2bf(s * 0.022097086912f); }
;     }
.LBB0_405:
	s_cmp_eq_u32 s49, 1
	v_readlane_b32 s4, v254, 28
	s_cselect_b64 s[2:3], -1, 0
	s_cmp_gt_u32 s4, 2
	s_cselect_b64 s[4:5], -1, 0
	s_and_b64 s[2:3], s[2:3], s[4:5]
	s_andn2_b64 vcc, exec, s[2:3]
	s_cbranch_vccnz .LBB0_412
	v_readlane_b32 s2, v254, 11
	v_mov_b32_e32 v0, v169
	s_add_i32 s2, s2, s62
	s_lshl_b32 s16, s2, 10
	v_ashrrev_i32_e32 v0, 6, v0
	v_readlane_b32 s2, v254, 29
	v_mov_b32_e32 v1, v169
	v_readlane_b32 s3, v254, 30
	v_lshl_add_u32 v0, s2, 3, v0
	v_cmp_gt_i32_e32 vcc, s16, v0
	s_and_saveexec_b64 s[2:3], vcc
	s_cbranch_execz .LBB0_411
	v_cmp_lt_i32_e32 vcc, v230, v219
	v_and_b32_e32 v10, 63, v1
	s_ashr_i32 s63, s62, 31
	v_cndmask_b32_e32 v1, v213, v230, vcc
	v_cmp_lt_i32_e32 vcc, v215, v219
	v_lshlrev_b32_e32 v4, 2, v1
	s_lshl_b64 s[4:5], s[62:63], 3
	v_cndmask_b32_e32 v1, v213, v215, vcc
	v_cmp_lt_i32_e32 vcc, v121, v219
	v_readlane_b32 s6, v254, 0
	v_lshlrev_b32_e32 v5, 2, v1
	v_cndmask_b32_e32 v1, v213, v121, vcc
	v_cmp_lt_i32_e32 vcc, v122, v219
	v_readlane_b32 s7, v254, 1
	s_add_u32 s4, s6, s4
	v_lshlrev_b32_e32 v6, 2, v1
	v_cndmask_b32_e32 v1, v213, v122, vcc
	v_cmp_lt_i32_e32 vcc, v123, v219
	s_addc_u32 s5, s7, s5
	v_lshlrev_b32_e32 v7, 2, v1
	v_cndmask_b32_e32 v1, v213, v123, vcc
	v_cmp_lt_i32_e32 vcc, v126, v219
	s_load_dwordx2 s[6:7], s[4:5], 0x140
	v_lshlrev_b32_e32 v8, 2, v1
	v_cndmask_b32_e32 v1, v213, v126, vcc
	v_lshlrev_b32_e32 v9, 2, v1
	s_lshl_b32 s8, s44, 3
	v_ashrrev_i32_e32 v1, 31, v0
	v_readlane_b32 s9, v254, 6
	v_lshlrev_b64 v[2:3], 13, v[0:1]
	s_add_u32 s10, s9, s62
	v_readlane_b32 s9, v254, 7
	v_lshl_or_b32 v2, v10, 4, v2
	s_addc_u32 s11, s9, s63
	s_ashr_i32 s9, s8, 31
	v_cmp_eq_u32_e64 s[4:5], 0, v10
	v_lshl_add_u64 v[2:3], s[10:11], 0, v[2:3]
	s_lshl_b64 s[10:11], s[8:9], 13
	s_mov_b64 s[12:13], 0
	global_load_dwordx4 v[12:15], v[2:3], off offset:-3072
	global_load_dwordx4 v[16:19], v[2:3], off offset:-2048
	global_load_dwordx4 v[20:23], v[2:3], off offset:-1024
	global_load_dwordx4 v[24:27], v[2:3], off
	s_branch .LBB0_409
.LBB0_408:
	s_or_b64 exec, exec, s[14:15]
	v_add_u32_e32 v0, s8, v0
	v_cmp_le_i32_e32 vcc, s16, v0
	s_or_b64 s[12:13], vcc, s[12:13]
	v_lshl_add_u64 v[2:3], v[2:3], 0, s[10:11]
	s_waitcnt vmcnt(0)
	v_mov_b32_e32 v12, v42
	v_mov_b32_e32 v13, v43
	v_mov_b32_e32 v14, v44
	v_mov_b32_e32 v15, v45
	v_mov_b32_e32 v16, v46
	v_mov_b32_e32 v17, v47
	v_mov_b32_e32 v18, v48
	v_mov_b32_e32 v19, v49
	v_mov_b32_e32 v20, v50
	v_mov_b32_e32 v21, v51
	v_mov_b32_e32 v22, v52
	v_mov_b32_e32 v23, v53
	v_mov_b32_e32 v24, v54
	v_mov_b32_e32 v25, v55
	v_mov_b32_e32 v26, v56
	v_mov_b32_e32 v27, v57
	s_andn2_b64 exec, exec, s[12:13]
	s_cbranch_execz .LBB0_411
.LBB0_409:
	v_add_u32_e32 v58, s8, v0
	v_cmp_gt_i32_e32 vcc, s16, v58
	v_lshl_add_u64 v[60:61], v[2:3], 0, s[10:11]
	s_nop 0
	v_cndmask_b32_e32 v60, v2, v60, vcc
	v_cndmask_b32_e32 v61, v3, v61, vcc
	global_load_dwordx4 v[42:45], v[60:61], off offset:-3072
	global_load_dwordx4 v[46:49], v[60:61], off offset:-2048
	global_load_dwordx4 v[50:53], v[60:61], off offset:-1024
	global_load_dwordx4 v[54:57], v[60:61], off
	s_waitcnt vmcnt(4)
	v_lshlrev_b32_e32 v1, 16, v12
	s_waitcnt lgkmcnt(0)
	v_and_b32_e32 v10, 0xffff0000, v12
	v_lshlrev_b32_e32 v12, 16, v13
	v_and_b32_e32 v13, 0xffff0000, v13
	v_sub_f32_e32 v1, v1, v10
	v_lshlrev_b32_e32 v28, 16, v14
	v_and_b32_e32 v14, 0xffff0000, v14
	v_sub_f32_e32 v10, v12, v13
	v_add_f32_e32 v1, 0, v1
	v_lshlrev_b32_e32 v29, 16, v15
	v_and_b32_e32 v15, 0xffff0000, v15
	v_sub_f32_e32 v12, v28, v14
	v_add_f32_e32 v1, v10, v1
	v_lshlrev_b32_e32 v30, 16, v16
	v_and_b32_e32 v16, 0xffff0000, v16
	v_sub_f32_e32 v13, v29, v15
	v_add_f32_e32 v1, v12, v1
	v_lshlrev_b32_e32 v31, 16, v17
	v_and_b32_e32 v17, 0xffff0000, v17
	v_sub_f32_e32 v14, v30, v16
	v_add_f32_e32 v1, v13, v1
	v_lshlrev_b32_e32 v32, 16, v18
	v_and_b32_e32 v18, 0xffff0000, v18
	v_sub_f32_e32 v15, v31, v17
	v_add_f32_e32 v1, v14, v1
	v_lshlrev_b32_e32 v33, 16, v19
	v_and_b32_e32 v19, 0xffff0000, v19
	v_sub_f32_e32 v16, v32, v18
	v_add_f32_e32 v1, v15, v1
	v_lshlrev_b32_e32 v34, 16, v20
	v_and_b32_e32 v20, 0xffff0000, v20
	v_sub_f32_e32 v17, v33, v19
	v_add_f32_e32 v1, v16, v1
	v_lshlrev_b32_e32 v35, 16, v21
	v_and_b32_e32 v21, 0xffff0000, v21
	v_sub_f32_e32 v18, v34, v20
	v_add_f32_e32 v1, v17, v1
	v_lshlrev_b32_e32 v36, 16, v22
	v_and_b32_e32 v22, 0xffff0000, v22
	v_sub_f32_e32 v19, v35, v21
	v_add_f32_e32 v1, v18, v1
	v_lshlrev_b32_e32 v37, 16, v23
	v_and_b32_e32 v23, 0xffff0000, v23
	v_sub_f32_e32 v20, v36, v22
	v_add_f32_e32 v1, v19, v1
	v_lshlrev_b32_e32 v38, 16, v24
	v_and_b32_e32 v24, 0xffff0000, v24
	v_sub_f32_e32 v21, v37, v23
	v_add_f32_e32 v1, v20, v1
	v_lshlrev_b32_e32 v39, 16, v25
	v_and_b32_e32 v25, 0xffff0000, v25
	v_sub_f32_e32 v22, v38, v24
	v_add_f32_e32 v1, v21, v1
	v_lshlrev_b32_e32 v40, 16, v26
	v_and_b32_e32 v26, 0xffff0000, v26
	v_sub_f32_e32 v23, v39, v25
	v_add_f32_e32 v1, v22, v1
	v_lshlrev_b32_e32 v41, 16, v27
	v_and_b32_e32 v27, 0xffff0000, v27
	v_sub_f32_e32 v24, v40, v26
	v_add_f32_e32 v1, v23, v1
	v_add_f32_e32 v1, v24, v1
	v_sub_f32_e32 v10, v41, v27
	v_add_f32_e32 v1, v10, v1
	ds_bpermute_b32 v10, v4, v1
	s_waitcnt lgkmcnt(0)
	v_add_f32_e32 v1, v1, v10
	ds_bpermute_b32 v10, v5, v1
	s_waitcnt lgkmcnt(0)
	v_add_f32_e32 v1, v1, v10
	ds_bpermute_b32 v10, v6, v1
	s_waitcnt lgkmcnt(0)
	v_add_f32_e32 v1, v1, v10
	ds_bpermute_b32 v10, v7, v1
	s_waitcnt lgkmcnt(0)
	v_add_f32_e32 v1, v1, v10
	ds_bpermute_b32 v10, v8, v1
	s_waitcnt lgkmcnt(0)
	v_add_f32_e32 v1, v1, v10
	ds_bpermute_b32 v10, v9, v1
	s_and_saveexec_b64 s[14:15], s[4:5]
	s_cbranch_execz .LBB0_408
	s_waitcnt lgkmcnt(0)
	v_add_f32_e32 v1, v1, v10
	v_mul_f32_e32 v1, 0x3cb504f3, v1
	v_ashrrev_i32_e32 v12, 10, v0
	v_bfe_u32 v13, v1, 16, 1
	v_add3_u32 v1, v1, v13, s95
	v_ashrrev_i32_e32 v13, 31, v12
	v_and_b32_e32 v10, 0x3ff, v0
	v_lshlrev_b64 v[12:13], 22, v[12:13]
	v_lshl_add_u64 v[12:13], s[6:7], 0, v[12:13]
	v_lshlrev_b32_e32 v10, 1, v10
	v_lshl_add_u64 v[12:13], v[12:13], 0, v[10:11]
	v_add_co_u32_e32 v12, vcc, 0x200000, v12
	s_nop 1
	v_addc_co_u32_e32 v13, vcc, 0, v13, vcc
	global_store_short_d16_hi v[12:13], v1, off
	s_branch .LBB0_408
